# sample LRU conv stage: 23 loads batched, branch-free state/Z row select (fma chain)
# baseline (speedup 1.0000x reference)
.LBB0_257:
	s_add_i32 s16, s25, 0xfffffa00
	s_mul_hi_u32 s17, s16, 0xaaaaaaab
	s_lshr_b32 s17, s17, 3
	s_mul_i32 s26, s17, 12
	s_lshl_b32 s40, s17, 7
	s_sub_i32 s38, s16, s26
	s_add_i32 s39, s40, 0x4000
	s_cmp_gt_u32 s38, 3
	s_mov_b64 s[16:17], -1
	s_barrier
	s_cbranch_scc0 .LBB0_287
	s_add_i32 s16, s38, -4
	s_lshl_b32 s26, s16, 7
	v_readlane_b32 s27, v253, 44
	v_mbcnt_lo_u32_b32 v97, -1, 0
	v_mbcnt_hi_u32_b32 v97, -1, v97
	s_add_i32 s17, s26, s27
	v_and_b32_e32 v101, 15, v97
	s_add_i32 s16, s16, s60
	v_or_b32_e32 v160, s17, v101
	s_ashr_i32 s17, s16, 31
	s_lshl_b64 s[16:17], s[16:17], 7
	s_add_u32 s16, s16, s27
	s_addc_u32 s17, s17, 0
	v_or_b32_e32 v6, s16, v101
	v_mov_b32_e32 v7, s17
	v_readlane_b32 s16, v253, 46
	v_lshl_add_u64 v[0:1], v[160:161], 2, s[72:73]
	v_lshlrev_b64 v[6:7], 8, v[6:7]
	v_readlane_b32 s17, v253, 47
	v_ashrrev_i32_e32 v99, 4, v97
	v_add_co_u32_e32 v2, vcc, 0x1000, v0
	v_lshl_add_u64 v[8:9], s[16:17], 0, v[6:7]
	v_lshlrev_b32_e32 v102, 3, v99
	v_readlane_b32 s16, v253, 48
	v_addc_co_u32_e32 v3, vcc, 0, v1, vcc
	v_ashrrev_i32_e32 v103, 31, v102
	v_readlane_b32 s17, v253, 49
	v_add_co_u32_e32 v4, vcc, 0x2000, v0
	v_lshlrev_b64 v[10:11], 1, v[102:103]
	v_lshl_add_u64 v[6:7], s[16:17], 0, v[6:7]
	v_addc_co_u32_e32 v5, vcc, 0, v1, vcc
	v_lshl_add_u64 v[32:33], v[8:9], 0, v[10:11]
	v_lshl_add_u64 v[6:7], v[6:7], 0, v[10:11]
	global_load_dword v98, v[0:1], off
	global_load_dword v100, v[2:3], off
	global_load_dword v96, v[4:5], off
	global_load_dwordx4 v[24:27], v[32:33], off
	global_load_dwordx4 v[16:19], v[32:33], off offset:64
	global_load_dwordx4 v[8:11], v[32:33], off offset:128
	global_load_dwordx4 v[20:23], v[6:7], off offset:64
	global_load_dwordx4 v[12:15], v[6:7], off offset:128
	global_load_dwordx4 v[28:31], v[6:7], off
	global_load_dwordx4 v[0:3], v[32:33], off offset:192
	s_nop 0
	global_load_dwordx4 v[4:7], v[6:7], off offset:192
	v_readlane_b32 s50, v252, 6
	v_readlane_b32 s51, v252, 7
	v_readlane_b32 s52, v252, 8
	v_readlane_b32 s53, v252, 9
	v_lshlrev_b32_e32 v194, 3, v101
	v_or_b32_e32 v194, s26, v194
	v_lshlrev_b32_e32 v195, 2, v194
	v_add_u32_e32 v197, s3, v97
	v_lshrrev_b32_e32 v198, 5, v197
	s_lshr_b32 s16, s40, 3
	v_add_u32_e32 v198, s16, v198
	global_load_dwordx4 v[32:35], v195, s[30:31]
	global_load_dwordx4 v[36:39], v195, s[30:31] offset:16
	v_add_u32_e32 v196, 0x1000, v195
	global_load_dwordx4 v[40:43], v196, s[30:31]
	global_load_dwordx4 v[44:47], v196, s[30:31] offset:16
	v_add_u32_e32 v196, 0x2000, v195
	global_load_dwordx4 v[48:51], v196, s[30:31]
	global_load_dwordx4 v[52:55], v196, s[30:31] offset:16
	v_add_u32_e32 v196, 0x3000, v195
	global_load_dwordx4 v[56:59], v196, s[30:31]
	global_load_dwordx4 v[60:63], v196, s[30:31] offset:16
	global_load_dwordx4 v[64:67], v195, s[64:65]
	global_load_dwordx4 v[68:71], v195, s[64:65] offset:16
	v_add_u32_e32 v199, s6, v198
	v_mul_u32_u24_e32 v199, 0x3000, v199
	v_add_u32_e32 v199, v199, v195
	global_load_dwordx4 v[72:75], v199, s[50:51]
	global_load_dwordx4 v[76:79], v199, s[50:51] offset:16
	v_add_u32_e32 v196, 0x1000, v199
	global_load_dwordx4 v[80:83], v196, s[50:51]
	global_load_dwordx4 v[84:87], v196, s[50:51] offset:16
	v_add_u32_e32 v196, 0x2000, v199
	global_load_dwordx4 v[88:91], v196, s[50:51]
	global_load_dwordx4 v[92:95], v196, s[50:51] offset:16
	v_lshlrev_b32_e32 v201, 3, v198
	v_bfe_u32 v202, v197, 4, 1
	v_lshlrev_b32_e32 v202, 2, v202
	v_lshlrev_b32_e32 v203, 1, v194
	v_add_u32_e32 v203, 0x8000800, v203
	v_add_u32_e32 v204, -3, v202
	v_max_i32_e32 v204, 0, v204
	v_add_u32_e32 v204, v204, v201
	v_lshl_add_u32 v204, v204, 13, v203
	global_load_dwordx4 v[104:107], v204, s[0:1]
	v_add_u32_e32 v204, -2, v202
	v_max_i32_e32 v204, 0, v204
	v_add_u32_e32 v204, v204, v201
	v_lshl_add_u32 v204, v204, 13, v203
	global_load_dwordx4 v[108:111], v204, s[0:1]
	v_add_u32_e32 v204, -1, v202
	v_max_i32_e32 v204, 0, v204
	v_add_u32_e32 v204, v204, v201
	v_lshl_add_u32 v204, v204, 13, v203
	global_load_dwordx4 v[112:115], v204, s[0:1]
	v_add_u32_e32 v204, 0, v202
	v_max_i32_e32 v204, 0, v204
	v_add_u32_e32 v204, v204, v201
	v_lshl_add_u32 v204, v204, 13, v203
	global_load_dwordx4 v[116:119], v204, s[0:1]
	v_add_u32_e32 v204, 1, v202
	v_max_i32_e32 v204, 0, v204
	v_add_u32_e32 v204, v204, v201
	v_lshl_add_u32 v204, v204, 13, v203
	global_load_dwordx4 v[120:123], v204, s[0:1]
	v_add_u32_e32 v204, 2, v202
	v_max_i32_e32 v204, 0, v204
	v_add_u32_e32 v204, v204, v201
	v_lshl_add_u32 v204, v204, 13, v203
	global_load_dwordx4 v[124:127], v204, s[0:1]
	v_add_u32_e32 v204, 3, v202
	v_max_i32_e32 v204, 0, v204
	v_add_u32_e32 v204, v204, v201
	v_lshl_add_u32 v204, v204, 13, v203
	global_load_dwordx4 v[128:131], v204, s[0:1]
	v_lshrrev_b32_e32 v200, 4, v197
	v_mul_u32_u24_e32 v200, 0x440, v200
	v_lshl_add_u32 v200, v101, 4, v200
	s_mov_b32 s27, 0xffff0000
	v_cmp_eq_u32_e32 vcc, 0, v202
	s_waitcnt vmcnt(0)
	v_lshlrev_b32_e32 v186, 16, v104
	v_and_b32_e32 v187, s27, v104
	v_lshlrev_b32_e32 v188, 16, v105
	v_and_b32_e32 v189, s27, v105
	v_lshlrev_b32_e32 v190, 16, v106
	v_and_b32_e32 v191, s27, v106
	v_lshlrev_b32_e32 v192, 16, v107
	v_and_b32_e32 v193, s27, v107
	v_cndmask_b32_e32 v186, v186, v72, vcc
	v_cndmask_b32_e32 v187, v187, v73, vcc
	v_cndmask_b32_e32 v188, v188, v74, vcc
	v_cndmask_b32_e32 v189, v189, v75, vcc
	v_cndmask_b32_e32 v190, v190, v76, vcc
	v_cndmask_b32_e32 v191, v191, v77, vcc
	v_cndmask_b32_e32 v192, v192, v78, vcc
	v_cndmask_b32_e32 v193, v193, v79, vcc
	v_pk_fma_f32 v[132:133], v[186:187], v[32:33], v[64:65]
	v_pk_fma_f32 v[134:135], v[188:189], v[34:35], v[66:67]
	v_pk_fma_f32 v[136:137], v[190:191], v[36:37], v[68:69]
	v_pk_fma_f32 v[138:139], v[192:193], v[38:39], v[70:71]
	v_lshlrev_b32_e32 v186, 16, v108
	v_and_b32_e32 v187, s27, v108
	v_lshlrev_b32_e32 v188, 16, v109
	v_and_b32_e32 v189, s27, v109
	v_lshlrev_b32_e32 v190, 16, v110
	v_and_b32_e32 v191, s27, v110
	v_lshlrev_b32_e32 v192, 16, v111
	v_and_b32_e32 v193, s27, v111
	v_cndmask_b32_e32 v186, v186, v80, vcc
	v_cndmask_b32_e32 v187, v187, v81, vcc
	v_cndmask_b32_e32 v188, v188, v82, vcc
	v_cndmask_b32_e32 v189, v189, v83, vcc
	v_cndmask_b32_e32 v190, v190, v84, vcc
	v_cndmask_b32_e32 v191, v191, v85, vcc
	v_cndmask_b32_e32 v192, v192, v86, vcc
	v_cndmask_b32_e32 v193, v193, v87, vcc
	v_pk_fma_f32 v[132:133], v[186:187], v[40:41], v[132:133]
	v_pk_fma_f32 v[134:135], v[188:189], v[42:43], v[134:135]
	v_pk_fma_f32 v[136:137], v[190:191], v[44:45], v[136:137]
	v_pk_fma_f32 v[138:139], v[192:193], v[46:47], v[138:139]
	v_pk_fma_f32 v[140:141], v[186:187], v[32:33], v[64:65]
	v_pk_fma_f32 v[142:143], v[188:189], v[34:35], v[66:67]
	v_pk_fma_f32 v[144:145], v[190:191], v[36:37], v[68:69]
	v_pk_fma_f32 v[146:147], v[192:193], v[38:39], v[70:71]
	v_lshlrev_b32_e32 v186, 16, v112
	v_and_b32_e32 v187, s27, v112
	v_lshlrev_b32_e32 v188, 16, v113
	v_and_b32_e32 v189, s27, v113
	v_lshlrev_b32_e32 v190, 16, v114
	v_and_b32_e32 v191, s27, v114
	v_lshlrev_b32_e32 v192, 16, v115
	v_and_b32_e32 v193, s27, v115
	v_cndmask_b32_e32 v186, v186, v88, vcc
	v_cndmask_b32_e32 v187, v187, v89, vcc
	v_cndmask_b32_e32 v188, v188, v90, vcc
	v_cndmask_b32_e32 v189, v189, v91, vcc
	v_cndmask_b32_e32 v190, v190, v92, vcc
	v_cndmask_b32_e32 v191, v191, v93, vcc
	v_cndmask_b32_e32 v192, v192, v94, vcc
	v_cndmask_b32_e32 v193, v193, v95, vcc
	v_pk_fma_f32 v[132:133], v[186:187], v[48:49], v[132:133]
	v_pk_fma_f32 v[134:135], v[188:189], v[50:51], v[134:135]
	v_pk_fma_f32 v[136:137], v[190:191], v[52:53], v[136:137]
	v_pk_fma_f32 v[138:139], v[192:193], v[54:55], v[138:139]
	v_pk_fma_f32 v[140:141], v[186:187], v[40:41], v[140:141]
	v_pk_fma_f32 v[142:143], v[188:189], v[42:43], v[142:143]
	v_pk_fma_f32 v[144:145], v[190:191], v[44:45], v[144:145]
	v_pk_fma_f32 v[146:147], v[192:193], v[46:47], v[146:147]
	v_pk_fma_f32 v[148:149], v[186:187], v[32:33], v[64:65]
	v_pk_fma_f32 v[150:151], v[188:189], v[34:35], v[66:67]
	v_pk_fma_f32 v[152:153], v[190:191], v[36:37], v[68:69]
	v_pk_fma_f32 v[154:155], v[192:193], v[38:39], v[70:71]
	v_lshlrev_b32_e32 v186, 16, v116
	v_and_b32_e32 v187, s27, v116
	v_lshlrev_b32_e32 v188, 16, v117
	v_and_b32_e32 v189, s27, v117
	v_lshlrev_b32_e32 v190, 16, v118
	v_and_b32_e32 v191, s27, v118
	v_lshlrev_b32_e32 v192, 16, v119
	v_and_b32_e32 v193, s27, v119
	v_pk_fma_f32 v[132:133], v[186:187], v[56:57], v[132:133]
	v_pk_fma_f32 v[134:135], v[188:189], v[58:59], v[134:135]
	v_pk_fma_f32 v[136:137], v[190:191], v[60:61], v[136:137]
	v_pk_fma_f32 v[138:139], v[192:193], v[62:63], v[138:139]
	v_pk_fma_f32 v[140:141], v[186:187], v[48:49], v[140:141]
	v_pk_fma_f32 v[142:143], v[188:189], v[50:51], v[142:143]
	v_pk_fma_f32 v[144:145], v[190:191], v[52:53], v[144:145]
	v_pk_fma_f32 v[146:147], v[192:193], v[54:55], v[146:147]
	v_pk_fma_f32 v[148:149], v[186:187], v[40:41], v[148:149]
	v_pk_fma_f32 v[150:151], v[188:189], v[42:43], v[150:151]
	v_pk_fma_f32 v[152:153], v[190:191], v[44:45], v[152:153]
	v_pk_fma_f32 v[154:155], v[192:193], v[46:47], v[154:155]
	v_pk_fma_f32 v[162:163], v[186:187], v[32:33], v[64:65]
	v_pk_fma_f32 v[164:165], v[188:189], v[34:35], v[66:67]
	v_pk_fma_f32 v[166:167], v[190:191], v[36:37], v[68:69]
	v_pk_fma_f32 v[168:169], v[192:193], v[38:39], v[70:71]
	v_lshlrev_b32_e32 v186, 16, v120
	v_and_b32_e32 v187, s27, v120
	v_lshlrev_b32_e32 v188, 16, v121
	v_and_b32_e32 v189, s27, v121
	v_lshlrev_b32_e32 v190, 16, v122
	v_and_b32_e32 v191, s27, v122
	v_lshlrev_b32_e32 v192, 16, v123
	v_and_b32_e32 v193, s27, v123
	v_pk_fma_f32 v[140:141], v[186:187], v[56:57], v[140:141]
	v_pk_fma_f32 v[142:143], v[188:189], v[58:59], v[142:143]
	v_pk_fma_f32 v[144:145], v[190:191], v[60:61], v[144:145]
	v_pk_fma_f32 v[146:147], v[192:193], v[62:63], v[146:147]
	v_pk_fma_f32 v[148:149], v[186:187], v[48:49], v[148:149]
	v_pk_fma_f32 v[150:151], v[188:189], v[50:51], v[150:151]
	v_pk_fma_f32 v[152:153], v[190:191], v[52:53], v[152:153]
	v_pk_fma_f32 v[154:155], v[192:193], v[54:55], v[154:155]
	v_pk_fma_f32 v[162:163], v[186:187], v[40:41], v[162:163]
	v_pk_fma_f32 v[164:165], v[188:189], v[42:43], v[164:165]
	v_pk_fma_f32 v[166:167], v[190:191], v[44:45], v[166:167]
	v_pk_fma_f32 v[168:169], v[192:193], v[46:47], v[168:169]
	v_lshlrev_b32_e32 v186, 16, v124
	v_and_b32_e32 v187, s27, v124
	v_lshlrev_b32_e32 v188, 16, v125
	v_and_b32_e32 v189, s27, v125
	v_lshlrev_b32_e32 v190, 16, v126
	v_and_b32_e32 v191, s27, v126
	v_lshlrev_b32_e32 v192, 16, v127
	v_and_b32_e32 v193, s27, v127
	v_pk_fma_f32 v[148:149], v[186:187], v[56:57], v[148:149]
	v_pk_fma_f32 v[150:151], v[188:189], v[58:59], v[150:151]
	v_pk_fma_f32 v[152:153], v[190:191], v[60:61], v[152:153]
	v_pk_fma_f32 v[154:155], v[192:193], v[62:63], v[154:155]
	v_pk_fma_f32 v[162:163], v[186:187], v[48:49], v[162:163]
	v_pk_fma_f32 v[164:165], v[188:189], v[50:51], v[164:165]
	v_pk_fma_f32 v[166:167], v[190:191], v[52:53], v[166:167]
	v_pk_fma_f32 v[168:169], v[192:193], v[54:55], v[168:169]
	v_lshlrev_b32_e32 v186, 16, v128
	v_and_b32_e32 v187, s27, v128
	v_lshlrev_b32_e32 v188, 16, v129
	v_and_b32_e32 v189, s27, v129
	v_lshlrev_b32_e32 v190, 16, v130
	v_and_b32_e32 v191, s27, v130
	v_lshlrev_b32_e32 v192, 16, v131
	v_and_b32_e32 v193, s27, v131
	v_pk_fma_f32 v[162:163], v[186:187], v[56:57], v[162:163]
	v_pk_fma_f32 v[164:165], v[188:189], v[58:59], v[164:165]
	v_pk_fma_f32 v[166:167], v[190:191], v[60:61], v[166:167]
	v_pk_fma_f32 v[168:169], v[192:193], v[62:63], v[168:169]
	v_cvt_pk_bf16_f32 v204, v132, v133
	v_cvt_pk_bf16_f32 v205, v134, v135
	v_cvt_pk_bf16_f32 v206, v136, v137
	v_cvt_pk_bf16_f32 v207, v138, v139
	ds_write_b128 v200, v[204:207]
	v_cvt_pk_bf16_f32 v204, v140, v141
	v_cvt_pk_bf16_f32 v205, v142, v143
	v_cvt_pk_bf16_f32 v206, v144, v145
	v_cvt_pk_bf16_f32 v207, v146, v147
	ds_write_b128 v200, v[204:207] offset:272
	v_cvt_pk_bf16_f32 v204, v148, v149
	v_cvt_pk_bf16_f32 v205, v150, v151
	v_cvt_pk_bf16_f32 v206, v152, v153
	v_cvt_pk_bf16_f32 v207, v154, v155
	ds_write_b128 v200, v[204:207] offset:544
	v_cvt_pk_bf16_f32 v204, v162, v163
	v_cvt_pk_bf16_f32 v205, v164, v165
	v_cvt_pk_bf16_f32 v206, v166, v167
	v_cvt_pk_bf16_f32 v207, v168, v169
	ds_write_b128 v200, v[204:207] offset:816
	v_lshl_add_u64 v[128:129], v[160:161], 2, s[52:53]
	s_lshr_b32 s26, s40, 3
	v_lshlrev_b32_e32 v32, 1, v102
	v_mul_u32_u24_e32 v33, 0x110, v101
	v_add3_u32 v114, 0, v32, v33
	s_waitcnt lgkmcnt(0)
	s_barrier
	ds_read_b128 v[32:35], v114
	ds_read_b128 v[40:43], v114 offset:4352
	ds_read_b128 v[48:51], v114 offset:8704
	ds_read_b128 v[56:59], v114 offset:13056
	ds_read_b128 v[64:67], v114 offset:17408
	ds_read_b128 v[72:75], v114 offset:21760
	ds_read_b128 v[80:83], v114 offset:26112
	ds_read_b128 v[88:91], v114 offset:30464
	s_waitcnt lgkmcnt(7)
	v_mfma_f32_16x16x32_bf16 v[36:39], v[32:35], v[24:27], 0
	s_movk_i32 s16, 0x440
	v_mfma_f32_16x16x32_bf16 v[32:35], v[32:35], v[28:31], 0
	s_waitcnt lgkmcnt(6)
	v_mfma_f32_16x16x32_bf16 v[44:47], v[40:43], v[24:27], 0
	v_mfma_f32_16x16x32_bf16 v[40:43], v[40:43], v[28:31], 0
	s_waitcnt lgkmcnt(5)
	v_mfma_f32_16x16x32_bf16 v[52:55], v[48:51], v[24:27], 0
	v_mfma_f32_16x16x32_bf16 v[48:51], v[48:51], v[28:31], 0
	s_waitcnt lgkmcnt(4)
	v_mfma_f32_16x16x32_bf16 v[60:63], v[56:59], v[24:27], 0
	v_mfma_f32_16x16x32_bf16 v[56:59], v[56:59], v[28:31], 0
	s_waitcnt lgkmcnt(3)
	v_mfma_f32_16x16x32_bf16 v[68:71], v[64:67], v[24:27], 0
	v_mfma_f32_16x16x32_bf16 v[64:67], v[64:67], v[28:31], 0
	s_waitcnt lgkmcnt(2)
	v_mfma_f32_16x16x32_bf16 v[76:79], v[72:75], v[24:27], 0
	v_mfma_f32_16x16x32_bf16 v[72:75], v[72:75], v[28:31], 0
	s_waitcnt lgkmcnt(1)
	v_mfma_f32_16x16x32_bf16 v[84:87], v[80:83], v[24:27], 0
	v_mfma_f32_16x16x32_bf16 v[80:83], v[80:83], v[28:31], 0
	s_waitcnt lgkmcnt(0)
	v_mfma_f32_16x16x32_bf16 v[24:27], v[88:91], v[24:27], 0
	v_mfma_f32_16x16x32_bf16 v[28:31], v[88:91], v[28:31], 0
	ds_read_b128 v[88:91], v114 offset:64
	s_waitcnt lgkmcnt(0)
	v_mfma_f32_16x16x32_bf16 v[36:39], v[88:91], v[16:19], v[36:39]
	v_mfma_f32_16x16x32_bf16 v[32:35], v[88:91], v[20:23], v[32:35]
	ds_read_b128 v[88:91], v114 offset:4416
	s_waitcnt lgkmcnt(0)
	v_mfma_f32_16x16x32_bf16 v[44:47], v[88:91], v[16:19], v[44:47]
	v_mfma_f32_16x16x32_bf16 v[40:43], v[88:91], v[20:23], v[40:43]
	ds_read_b128 v[88:91], v114 offset:8768
	s_waitcnt lgkmcnt(0)
	v_mfma_f32_16x16x32_bf16 v[52:55], v[88:91], v[16:19], v[52:55]
	v_mfma_f32_16x16x32_bf16 v[48:51], v[88:91], v[20:23], v[48:51]
	ds_read_b128 v[88:91], v114 offset:13120
	s_waitcnt lgkmcnt(0)
	v_mfma_f32_16x16x32_bf16 v[60:63], v[88:91], v[16:19], v[60:63]
	v_mfma_f32_16x16x32_bf16 v[56:59], v[88:91], v[20:23], v[56:59]
	ds_read_b128 v[88:91], v114 offset:17472
	s_waitcnt lgkmcnt(0)
	v_mfma_f32_16x16x32_bf16 v[68:71], v[88:91], v[16:19], v[68:71]
	v_mfma_f32_16x16x32_bf16 v[64:67], v[88:91], v[20:23], v[64:67]
	ds_read_b128 v[88:91], v114 offset:21824
	s_waitcnt lgkmcnt(0)
	v_mfma_f32_16x16x32_bf16 v[76:79], v[88:91], v[16:19], v[76:79]
	v_mfma_f32_16x16x32_bf16 v[72:75], v[88:91], v[20:23], v[72:75]
	ds_read_b128 v[88:91], v114 offset:26176
	s_waitcnt lgkmcnt(0)
	v_mfma_f32_16x16x32_bf16 v[84:87], v[88:91], v[16:19], v[84:87]
	v_mfma_f32_16x16x32_bf16 v[80:83], v[88:91], v[20:23], v[80:83]
	ds_read_b128 v[88:91], v114 offset:30528
	s_waitcnt lgkmcnt(0)
	v_mfma_f32_16x16x32_bf16 v[16:19], v[88:91], v[16:19], v[24:27]
	s_nop 2
	ds_read_b128 v[24:27], v114 offset:128
	v_mfma_f32_16x16x32_bf16 v[20:23], v[88:91], v[20:23], v[28:31]
	s_waitcnt lgkmcnt(0)
	v_mfma_f32_16x16x32_bf16 v[28:31], v[24:27], v[8:11], v[36:39]
	v_mfma_f32_16x16x32_bf16 v[24:27], v[24:27], v[12:15], v[32:35]
	s_nop 2
	ds_read_b128 v[32:35], v114 offset:4480
	s_waitcnt lgkmcnt(0)
	v_mfma_f32_16x16x32_bf16 v[36:39], v[32:35], v[8:11], v[44:47]
	v_mfma_f32_16x16x32_bf16 v[32:35], v[32:35], v[12:15], v[40:43]
	s_nop 2
	ds_read_b128 v[40:43], v114 offset:8832
	s_waitcnt lgkmcnt(0)
	v_mfma_f32_16x16x32_bf16 v[44:47], v[40:43], v[8:11], v[52:55]
	v_mfma_f32_16x16x32_bf16 v[88:91], v[40:43], v[12:15], v[48:51]
	ds_read_b128 v[40:43], v114 offset:13184
	s_waitcnt lgkmcnt(0)
	v_mfma_f32_16x16x32_bf16 v[92:95], v[40:43], v[8:11], v[60:63]
	v_mfma_f32_16x16x32_bf16 v[102:105], v[40:43], v[12:15], v[56:59]
	ds_read_b128 v[40:43], v114 offset:17536
	s_waitcnt lgkmcnt(0)
	v_mfma_f32_16x16x32_bf16 v[68:71], v[40:43], v[8:11], v[68:71]
	v_mfma_f32_16x16x32_bf16 v[64:67], v[40:43], v[12:15], v[64:67]
	ds_read_b128 v[40:43], v114 offset:21888
	s_waitcnt lgkmcnt(0)
	v_mfma_f32_16x16x32_bf16 v[76:79], v[40:43], v[8:11], v[76:79]
	v_mfma_f32_16x16x32_bf16 v[72:75], v[40:43], v[12:15], v[72:75]
	ds_read_b128 v[40:43], v114 offset:26240
	s_waitcnt lgkmcnt(0)
	v_mfma_f32_16x16x32_bf16 v[84:87], v[40:43], v[8:11], v[84:87]
	v_mfma_f32_16x16x32_bf16 v[80:83], v[40:43], v[12:15], v[80:83]
	ds_read_b128 v[40:43], v114 offset:30592
	s_waitcnt lgkmcnt(0)
	v_mfma_f32_16x16x32_bf16 v[106:109], v[40:43], v[8:11], v[16:19]
	ds_read_b128 v[8:11], v114 offset:192
	v_mfma_f32_16x16x32_bf16 v[110:113], v[40:43], v[12:15], v[20:23]
	ds_read_b128 v[12:15], v114 offset:26304
	s_waitcnt lgkmcnt(1)
	v_mfma_f32_16x16x32_bf16 v[56:59], v[8:11], v[0:3], v[28:31]
	v_mfma_f32_16x16x32_bf16 v[60:63], v[8:11], v[4:7], v[24:27]
	ds_read_b128 v[8:11], v114 offset:4544
	s_nop 5
	v_pk_add_f32 v[56:57], v[98:99], v[56:57] op_sel_hi:[0,1]
	v_exp_f32_e32 v56, v56
	s_waitcnt lgkmcnt(0)
	v_mfma_f32_16x16x32_bf16 v[48:51], v[8:11], v[0:3], v[36:39]
	v_exp_f32_e32 v57, v57
	v_pk_add_f32 v[60:61], v[100:101], v[60:61] op_sel_hi:[0,1]
	v_exp_f32_e32 v60, v60
	v_mfma_f32_16x16x32_bf16 v[52:55], v[8:11], v[4:7], v[32:35]
	ds_read_b128 v[8:11], v114 offset:8896
	v_pk_add_f32 v[56:57], v[56:57], 1.0 op_sel_hi:[1,0]
	v_exp_f32_e32 v61, v61
	s_waitcnt lgkmcnt(0)
	v_mfma_f32_16x16x32_bf16 v[40:43], v[8:11], v[0:3], v[44:47]
	v_rcp_f32_e32 v56, v56
	v_rcp_f32_e32 v57, v57
	v_pk_add_f32 v[58:59], v[98:99], v[58:59] op_sel_hi:[0,1]
	v_mfma_f32_16x16x32_bf16 v[44:47], v[8:11], v[4:7], v[88:91]
	ds_read_b128 v[8:11], v114 offset:13248
	v_pk_mul_f32 v[56:57], v[96:97], v[56:57] op_sel_hi:[0,1]
	v_exp_f32_e32 v132, v56
	s_waitcnt lgkmcnt(0)
	v_mfma_f32_16x16x32_bf16 v[32:35], v[8:11], v[0:3], v[92:95]
	v_exp_f32_e32 v133, v57
	v_exp_f32_e32 v58, v58
	v_exp_f32_e32 v59, v59
	v_mfma_f32_16x16x32_bf16 v[36:39], v[8:11], v[4:7], v[102:105]
	ds_read_b128 v[8:11], v114 offset:17600
	v_pk_add_f32 v[60:61], v[60:61], 1.0 op_sel_hi:[1,0]
	v_pk_fma_f32 v[56:57], v[132:133], v[132:133], 1.0 op_sel_hi:[1,1,0] neg_lo:[1,0,0] neg_hi:[1,0,0]
	s_waitcnt lgkmcnt(0)
	v_mfma_f32_16x16x32_bf16 v[24:27], v[8:11], v[0:3], v[68:71]
	v_rcp_f32_e32 v60, v60
	v_rcp_f32_e32 v61, v61
	v_max_f32_e32 v56, 0x2b8cbccc, v56
	v_mfma_f32_16x16x32_bf16 v[28:31], v[8:11], v[4:7], v[64:67]
	ds_read_b128 v[8:11], v114 offset:21952
	v_max_f32_e32 v57, 0x2b8cbccc, v57
	v_pk_add_f32 v[58:59], v[58:59], 1.0 op_sel_hi:[1,0]
	ds_read_b128 v[64:67], v114 offset:30656
	s_waitcnt lgkmcnt(1)
	v_mfma_f32_16x16x32_bf16 v[16:19], v[8:11], v[0:3], v[76:79]
	v_sqrt_f32_e32 v56, v56
	v_sqrt_f32_e32 v57, v57
	v_rcp_f32_e32 v58, v58
	v_mfma_f32_16x16x32_bf16 v[20:23], v[8:11], v[4:7], v[72:75]
	v_rcp_f32_e32 v59, v59
	s_nop 0
	v_pk_mul_f32 v[58:59], v[96:97], v[58:59] op_sel_hi:[0,1]
	v_mfma_f32_16x16x32_bf16 v[8:11], v[12:15], v[0:3], v[84:87]
	v_exp_f32_e32 v136, v58
	v_exp_f32_e32 v137, v59
	v_mfma_f32_16x16x32_bf16 v[12:15], v[12:15], v[4:7], v[80:83]
	v_fma_f32 v58, -v136, v136, 1.0
	v_fma_f32 v59, -v137, v137, 1.0
	v_max_f32_e32 v58, 0x2b8cbccc, v58
	s_waitcnt lgkmcnt(0)
	v_mfma_f32_16x16x32_bf16 v[0:3], v[64:67], v[0:3], v[106:109]
	v_max_f32_e32 v59, 0x2b8cbccc, v59
	v_sqrt_f32_e32 v58, v58
	v_sqrt_f32_e32 v59, v59
	v_mfma_f32_16x16x32_bf16 v[4:7], v[64:67], v[4:7], v[110:113]
	v_mul_lo_u32 v64, v99, s16
	v_lshlrev_b32_e32 v65, 1, v101
	v_readlane_b32 s16, v254, 52
	s_nop 1
	v_add3_u32 v66, s16, v64, v65
	ds_read_u16 v64, v66
	ds_read_u16 v65, v66 offset:272
	s_lshl_b32 s16, s39, 12
	s_waitcnt lgkmcnt(1)
	v_lshlrev_b32_e32 v64, 16, v64
	s_waitcnt lgkmcnt(0)
	v_lshlrev_b32_e32 v65, 16, v65
	v_pk_mul_f32 v[60:61], v[60:61], v[64:65]
	s_nop 0
	v_pk_mul_f32 v[134:135], v[56:57], v[60:61]
	v_pk_add_f32 v[60:61], v[100:101], v[62:63] op_sel_hi:[0,1]
	v_exp_f32_e32 v60, v60
	v_exp_f32_e32 v61, v61
	ds_read_u16 v56, v66 offset:544
	ds_read_u16 v57, v66 offset:816
	v_fma_f32 v134, 0, v132, v134
	v_pk_add_f32 v[60:61], v[60:61], 1.0 op_sel_hi:[1,0]
	v_fmac_f32_e32 v135, v133, v134
	v_rcp_f32_e32 v60, v60
	v_rcp_f32_e32 v61, v61
	s_waitcnt lgkmcnt(1)
	v_lshlrev_b32_e32 v56, 16, v56
	s_waitcnt lgkmcnt(0)
	v_lshlrev_b32_e32 v57, 16, v57
	v_mul_f32_e32 v133, v132, v133
	v_pk_mul_f32 v[56:57], v[60:61], v[56:57]
	s_nop 0
	v_pk_mul_f32 v[130:131], v[58:59], v[56:57]
	v_lshl_add_u32 v56, v99, 14, s16
	v_ashrrev_i32_e32 v99, 5, v97
	v_add_u32_e32 v126, s26, v99
	v_ashrrev_i32_e32 v127, 31, v126
	v_lshl_add_u64 v[138:139], s[6:7], 0, v[126:127]
	v_lshlrev_b64 v[156:157], 12, v[138:139]
	ds_read_u16 v117, v66 offset:4352
	ds_read_u16 v119, v66 offset:4624
	ds_read_u16 v113, v66 offset:4896
	ds_read_u16 v115, v66 offset:5168
	ds_read_u16 v109, v66 offset:8704
	ds_read_u16 v111, v66 offset:8976
	ds_read_u16 v105, v66 offset:9248
	ds_read_u16 v107, v66 offset:9520
	ds_read_u16 v95, v66 offset:13056
	ds_read_u16 v103, v66 offset:13328
	ds_read_u16 v91, v66 offset:13600
	ds_read_u16 v93, v66 offset:13872
	ds_read_u16 v87, v66 offset:17408
	ds_read_u16 v89, v66 offset:17680
	ds_read_u16 v83, v66 offset:17952
	ds_read_u16 v85, v66 offset:18224
	ds_read_u16 v79, v66 offset:21760
	ds_read_u16 v81, v66 offset:22032
	ds_read_u16 v75, v66 offset:22304
	ds_read_u16 v77, v66 offset:22576
	ds_read_u16 v71, v66 offset:26112
	ds_read_u16 v73, v66 offset:26384
	ds_read_u16 v67, v66 offset:26656
	ds_read_u16 v69, v66 offset:26928
	ds_read_u16 v61, v66 offset:30464
	ds_read_u16 v63, v66 offset:30736
	ds_read_u16 v57, v66 offset:31008
	ds_read_u16 v59, v66 offset:31280
	v_lshl_add_u64 v[156:157], v[128:129], 0, v[156:157]
	global_load_dword v101, v[156:157], off
	v_mov_b32_e32 v186, 0x2000
	v_mov_b32_e32 v187, 0
	v_lshl_add_u64 v[188:189], v[186:187], 0, v[156:157]
	global_load_dword v200, v[188:189], off
	v_lshl_add_u64 v[190:191], v[186:187], 0, v[188:189]
	global_load_dword v201, v[190:191], off
	v_lshl_add_u64 v[188:189], v[186:187], 0, v[190:191]
	global_load_dword v202, v[188:189], off
	v_lshl_add_u64 v[190:191], v[186:187], 0, v[188:189]
	global_load_dword v203, v[190:191], off
	v_lshl_add_u64 v[188:189], v[186:187], 0, v[190:191]
	global_load_dword v204, v[188:189], off
	v_lshl_add_u64 v[190:191], v[186:187], 0, v[188:189]
	global_load_dword v205, v[190:191], off
	v_lshl_add_u64 v[188:189], v[186:187], 0, v[190:191]
	global_load_dword v206, v[188:189], off
	v_add_lshl_u32 v65, v160, v56, 1
	v_add_u32_e32 v56, 0x1800, v65
	v_add_u32_e32 v58, 0x3800, v65
	v_add_u32_e32 v60, 0x5800, v65
	v_add_u32_e32 v62, 0x7800, v65
	v_add_u32_e32 v64, 0x21800, v65
	v_add_u32_e32 v66, 0x23800, v65
	v_add_u32_e32 v68, 0x25800, v65
	v_add_u32_e32 v70, 0x27800, v65
	v_add_u32_e32 v72, 0x41800, v65
	v_add_u32_e32 v74, 0x43800, v65
	v_add_u32_e32 v76, 0x45800, v65
	v_add_u32_e32 v78, 0x47800, v65
	v_add_u32_e32 v80, 0x61800, v65
	v_add_u32_e32 v82, 0x63800, v65
	v_add_u32_e32 v84, 0x65800, v65
	v_add_u32_e32 v86, 0x67800, v65
	v_add_u32_e32 v88, 0x81800, v65
	v_add_u32_e32 v90, 0x83800, v65
	v_add_u32_e32 v92, 0x85800, v65
	v_add_u32_e32 v94, 0x87800, v65
	v_add_u32_e32 v102, 0xa1800, v65
	v_add_u32_e32 v104, 0xa3800, v65
	v_add_u32_e32 v106, 0xa5800, v65
	v_add_u32_e32 v108, 0xa7800, v65
	v_add_u32_e32 v110, 0xc1800, v65
	v_add_u32_e32 v112, 0xc3800, v65
	v_add_u32_e32 v114, 0xc5800, v65
	v_add_u32_e32 v116, 0xc7800, v65
	v_add_u32_e32 v118, 0xe1800, v65
	v_add_u32_e32 v120, 0xe3800, v65
	v_add_u32_e32 v122, 0xe5800, v65
	v_add_u32_e32 v124, 0xe7800, v65
	global_load_ushort v182, v56, s[0:1]
	global_load_ushort v183, v58, s[0:1]
	global_load_ushort v184, v60, s[0:1]
	global_load_ushort v185, v62, s[0:1]
	global_load_ushort v178, v64, s[0:1]
	global_load_ushort v179, v66, s[0:1]
	global_load_ushort v180, v68, s[0:1]
	global_load_ushort v181, v70, s[0:1]
	global_load_ushort v174, v72, s[0:1]
	global_load_ushort v175, v74, s[0:1]
	global_load_ushort v176, v76, s[0:1]
	global_load_ushort v177, v78, s[0:1]
	global_load_ushort v170, v80, s[0:1]
	global_load_ushort v171, v82, s[0:1]
	global_load_ushort v172, v84, s[0:1]
	global_load_ushort v173, v86, s[0:1]
	global_load_ushort v152, v88, s[0:1]
	global_load_ushort v153, v90, s[0:1]
	global_load_ushort v154, v92, s[0:1]
	global_load_ushort v155, v94, s[0:1]
	global_load_ushort v148, v102, s[0:1]
	global_load_ushort v149, v104, s[0:1]
	global_load_ushort v150, v106, s[0:1]
	global_load_ushort v151, v108, s[0:1]
	global_load_ushort v144, v110, s[0:1]
	global_load_ushort v145, v112, s[0:1]
	global_load_ushort v146, v114, s[0:1]
	global_load_ushort v147, v116, s[0:1]
	global_load_ushort v140, v118, s[0:1]
	global_load_ushort v141, v120, s[0:1]
	global_load_ushort v142, v122, s[0:1]
	global_load_ushort v143, v124, s[0:1]
	v_lshl_add_u32 v65, v97, 2, v231
	v_fma_f32 v130, v136, v135, v130
	v_mul_f32_e32 v136, v136, v133
	v_and_b32_e32 v65, 0xfc, v65
	v_and_b32_e32 v97, 16, v97
	v_fmac_f32_e32 v131, v137, v130
	v_mul_f32_e32 v137, v137, v136
	v_cmp_eq_u32_e64 s[36:37], 0, v97
	v_cmp_ne_u32_e64 s[34:35], 0, v97
	ds_bpermute_b32 v97, v65, v137
	ds_bpermute_b32 v99, v65, v131
	s_waitcnt vmcnt(32) lgkmcnt(0)
	v_fmac_f32_e32 v99, v101, v97
	v_cndmask_b32_e64 v156, v99, v101, s[36:37]
	v_pk_fma_f32 v[130:131], v[136:137], v[156:157], v[130:131] op_sel_hi:[1,0,1]
	v_pk_fma_f32 v[132:133], v[132:133], v[156:157], v[134:135] op_sel_hi:[1,0,1]
	s_and_saveexec_b64 s[16:17], s[34:35]
	s_cbranch_execz .LBB0_272
	v_lshlrev_b64 v[134:135], 10, v[138:139]
	v_lshl_add_u64 v[134:135], v[134:135], 2, s[8:9]
	v_lshl_add_u64 v[134:135], v[160:161], 2, v[134:135]
	v_add_co_u32_e32 v134, vcc, 0x6a60000, v134
	s_nop 1
	v_addc_co_u32_e32 v135, vcc, 0, v135, vcc
	global_store_dword v[134:135], v131, off
